# adaLN items: the 18 conditioning loads per thread batched and staged raw in LDS, silu loop reads them back from LDS (phase 0 and background queue copies)
# speedup vs baseline: 1.0179x; 1.0006x over previous
; DI void p0_mod_item(const Params& P, unsigned char* lds, int idx, const int tid) {
;     ...
;   for (int i = tid; i < 9 * 1024; i += 512) {
;     int r = i >> 10, k = i & 1023;
;     float cv = r < 8 ? P.c[r * 1024 + k] : P.c_ctx[k];
;     sl[i] = cv / (1.f + expf(-cv));
;   }
.LBB0_1071:
	s_and_b64 vcc, exec, s[0:1]
	s_cbranch_vccz .LBB0_1086
	s_movk_i32 s0, 0x2400
	v_cmp_gt_i32_e32 vcc, s0, v56
	s_and_saveexec_b64 s[2:3], vcc
	s_cbranch_execz .LBB0_1080
	v_max_i32_e32 v0, 0x2200, v56
	v_sub_u32_e32 v0, v0, v56
	v_add_u32_e32 v0, 0x1ff, v0
	s_movk_i32 s0, 0x1ff
	v_cmp_lt_u32_e32 vcc, s0, v0
	s_mov_b64 s[0:1], -1
	v_mov_b32_e32 v2, v56
	s_and_saveexec_b64 s[4:5], vcc
	s_cbranch_execz .LBB0_1077
	v_lshrrev_b32_e32 v0, 9, v0
	v_add_u32_e32 v4, 1, v0
	v_and_b32_e32 v5, 0xfffffe, v4
	v_add_u32_e32 v57, 0x200, v56
	v_lshl_add_u32 v6, v56, 2, 0
	s_mov_b64 s[6:7], 0
	v_mov_b32_e32 v7, v5
	v_mov_b64_e32 v[2:3], v[56:57]
	s_mov_b32 s8, 0xbfb8aa3b
	s_mov_b32 s9, 0x42ce8ed0
	s_mov_b32 s11, 0xc2b17218
	s_mov_b32 s100, s74
	s_mov_b32 s101, s75
	global_load_dword v120, v6, s[100:101]
	global_load_dword v121, v6, s[100:101] offset:2048
	s_add_u32 s100, s100, 0x1000
	s_addc_u32 s101, s101, 0
	global_load_dword v122, v6, s[100:101]
	global_load_dword v123, v6, s[100:101] offset:2048
	s_add_u32 s100, s100, 0x1000
	s_addc_u32 s101, s101, 0
	global_load_dword v124, v6, s[100:101]
	global_load_dword v125, v6, s[100:101] offset:2048
	s_add_u32 s100, s100, 0x1000
	s_addc_u32 s101, s101, 0
	global_load_dword v126, v6, s[100:101]
	global_load_dword v127, v6, s[100:101] offset:2048
	s_add_u32 s100, s100, 0x1000
	s_addc_u32 s101, s101, 0
	global_load_dword v128, v6, s[100:101]
	global_load_dword v129, v6, s[100:101] offset:2048
	s_add_u32 s100, s100, 0x1000
	s_addc_u32 s101, s101, 0
	global_load_dword v130, v6, s[100:101]
	global_load_dword v131, v6, s[100:101] offset:2048
	s_add_u32 s100, s100, 0x1000
	s_addc_u32 s101, s101, 0
	global_load_dword v132, v6, s[100:101]
	global_load_dword v133, v6, s[100:101] offset:2048
	s_add_u32 s100, s100, 0x1000
	s_addc_u32 s101, s101, 0
	global_load_dword v134, v6, s[100:101]
	global_load_dword v135, v6, s[100:101] offset:2048
	global_load_dword v136, v6, s[78:79]
	global_load_dword v137, v6, s[78:79] offset:2048
	s_waitcnt vmcnt(17)
	ds_write_b32 v6, v120
	s_waitcnt vmcnt(16)
	ds_write_b32 v6, v121 offset:2048
	s_waitcnt vmcnt(15)
	ds_write_b32 v6, v122 offset:4096
	s_waitcnt vmcnt(14)
	ds_write_b32 v6, v123 offset:6144
	s_waitcnt vmcnt(13)
	ds_write_b32 v6, v124 offset:8192
	s_waitcnt vmcnt(12)
	ds_write_b32 v6, v125 offset:10240
	s_waitcnt vmcnt(11)
	ds_write_b32 v6, v126 offset:12288
	s_waitcnt vmcnt(10)
	ds_write_b32 v6, v127 offset:14336
	s_waitcnt vmcnt(9)
	ds_write_b32 v6, v128 offset:16384
	s_waitcnt vmcnt(8)
	ds_write_b32 v6, v129 offset:18432
	s_waitcnt vmcnt(7)
	ds_write_b32 v6, v130 offset:20480
	s_waitcnt vmcnt(6)
	ds_write_b32 v6, v131 offset:22528
	s_waitcnt vmcnt(5)
	ds_write_b32 v6, v132 offset:24576
	s_waitcnt vmcnt(4)
	ds_write_b32 v6, v133 offset:26624
	s_waitcnt vmcnt(3)
	ds_write_b32 v6, v134 offset:28672
	s_waitcnt vmcnt(2)
	ds_write_b32 v6, v135 offset:30720
	s_waitcnt vmcnt(1)
	ds_write_b32 v6, v136 offset:32768
	s_waitcnt vmcnt(0)
	ds_write_b32 v6, v137 offset:34816
.LBB0_1075:
	v_and_b32_e32 v0, 0x3ff, v2
	v_ashrrev_i32_e32 v11, 31, v2
	v_mov_b32_e32 v10, v2
	v_and_b32_e32 v14, 0x3ff, v3
	v_lshlrev_b32_e32 v0, 2, v0
	v_cmp_gt_i32_e32 vcc, s63, v2
	v_ashrrev_i32_e32 v9, 31, v3
	v_mov_b32_e32 v8, v3
	v_lshl_add_u64 v[10:11], v[10:11], 2, s[74:75]
	v_lshl_add_u64 v[12:13], s[78:79], 0, v[0:1]
	v_lshlrev_b32_e32 v0, 2, v14
	v_cmp_gt_i32_e64 s[0:1], s63, v3
	v_lshl_add_u64 v[8:9], v[8:9], 2, s[74:75]
	v_lshl_add_u64 v[14:15], s[78:79], 0, v[0:1]
	v_cndmask_b32_e32 v11, v13, v11, vcc
	v_cndmask_b32_e32 v10, v12, v10, vcc
	v_cndmask_b32_e64 v9, v15, v9, s[0:1]
	v_cndmask_b32_e64 v8, v14, v8, s[0:1]
	ds_read_b32 v0, v6
	s_nop 0
	ds_read_b32 v10, v6 offset:2048
	v_add_u32_e32 v7, -2, v7
	v_add_u32_e32 v3, 0x400, v3
	v_add_u32_e32 v2, 0x400, v2
	s_waitcnt lgkmcnt(0)
	v_mul_f32_e32 v8, 0xbfb8aa3b, v10
	v_fma_f32 v9, v10, s8, -v8
	v_rndne_f32_e32 v11, v8
	v_fmac_f32_e32 v9, 0xb2a5705f, v10
	v_sub_f32_e32 v8, v8, v11
	v_add_f32_e32 v8, v8, v9
	v_exp_f32_e32 v8, v8
	v_cvt_i32_f32_e32 v9, v11
	v_cmp_nlt_f32_e32 vcc, s9, v10
	v_ldexp_f32 v8, v8, v9
	s_nop 0
	v_cndmask_b32_e32 v8, 0, v8, vcc
	v_cmp_ngt_f32_e32 vcc, s11, v10
	s_nop 1
	v_cndmask_b32_e32 v9, v225, v8, vcc
	v_mul_f32_e32 v8, 0xbfb8aa3b, v0
	v_fma_f32 v11, v0, s8, -v8
	v_rndne_f32_e32 v12, v8
	v_fmac_f32_e32 v11, 0xb2a5705f, v0
	v_sub_f32_e32 v8, v8, v12
	v_add_f32_e32 v8, v8, v11
	v_exp_f32_e32 v8, v8
	v_cvt_i32_f32_e32 v11, v12
	v_cmp_nlt_f32_e32 vcc, s9, v0
	v_ldexp_f32 v8, v8, v11
	s_nop 0
	v_cndmask_b32_e32 v8, 0, v8, vcc
	v_cmp_ngt_f32_e32 vcc, s11, v0
	s_nop 1
	v_cndmask_b32_e32 v8, v225, v8, vcc
	v_pk_add_f32 v[8:9], v[8:9], 1.0 op_sel_hi:[1,0]
	s_nop 0
	v_div_scale_f32 v11, s[0:1], v9, v9, v10
	v_rcp_f32_e32 v12, v11
	s_nop 0
	v_fma_f32 v13, -v11, v12, 1.0
	v_fmac_f32_e32 v12, v13, v12
	v_div_scale_f32 v13, vcc, v10, v9, v10
	v_mul_f32_e32 v14, v13, v12
	v_fma_f32 v15, -v11, v14, v13
	v_fmac_f32_e32 v14, v15, v12
	v_fma_f32 v11, -v11, v14, v13
	v_div_fmas_f32 v11, v11, v12, v14
	v_div_fixup_f32 v9, v11, v9, v10
	v_div_scale_f32 v10, s[0:1], v8, v8, v0
	v_rcp_f32_e32 v11, v10
	s_nop 0
	v_fma_f32 v12, -v10, v11, 1.0
	v_fmac_f32_e32 v11, v12, v11
	v_div_scale_f32 v12, vcc, v0, v8, v0
	v_mul_f32_e32 v13, v12, v11
	v_fma_f32 v14, -v10, v13, v12
	v_fmac_f32_e32 v13, v14, v11
	v_fma_f32 v10, -v10, v13, v12
	v_div_fmas_f32 v10, v10, v11, v13
	v_div_fixup_f32 v0, v10, v8, v0
	v_cmp_eq_u32_e32 vcc, 0, v7
	ds_write2st64_b32 v6, v0, v9 offset1:8
	v_add_u32_e32 v6, 0x1000, v6
	s_or_b64 s[6:7], vcc, s[6:7]
	s_andn2_b64 exec, exec, s[6:7]
	s_cbranch_execnz .LBB0_1075
	s_or_b64 exec, exec, s[6:7]
	v_cmp_ne_u32_e32 vcc, v4, v5
	v_lshl_add_u32 v2, v5, 9, v56
	s_orn2_b64 s[0:1], vcc, exec

; DI void p0_mod_item(const Params& P, unsigned char* lds, int idx, const int tid) {
;     ...
;   for (int i = tid; i < 9 * 1024; i += 512) {
;     int r = i >> 10, k = i & 1023;
;     float cv = r < 8 ? P.c[r * 1024 + k] : P.c_ctx[k];
;     sl[i] = cv / (1.f + expf(-cv));
;   }
.LBB0_1227:
	s_and_saveexec_b64 s[2:3], s[38:39]
	s_cbranch_execz .LBB0_1237
	s_mov_b64 s[0:1], -1
	v_mov_b32_e32 v2, v54
	v_mov_b32_e32 v0, v66
	s_and_saveexec_b64 s[4:5], s[42:43]
	s_cbranch_execz .LBB0_1234
	s_mov_b64 s[6:7], 0
	v_mov_b32_e32 v4, v84
	v_mov_b32_e32 v5, v104
	v_mov_b64_e32 v[2:3], v[54:55]
	s_mov_b32 s100, s74
	s_mov_b32 s101, s75
	global_load_dword v120, v5, s[100:101]
	global_load_dword v121, v5, s[100:101] offset:2048
	s_add_u32 s100, s100, 0x1000
	s_addc_u32 s101, s101, 0
	global_load_dword v122, v5, s[100:101]
	global_load_dword v123, v5, s[100:101] offset:2048
	s_add_u32 s100, s100, 0x1000
	s_addc_u32 s101, s101, 0
	global_load_dword v124, v5, s[100:101]
	global_load_dword v125, v5, s[100:101] offset:2048
	s_add_u32 s100, s100, 0x1000
	s_addc_u32 s101, s101, 0
	global_load_dword v126, v5, s[100:101]
	global_load_dword v127, v5, s[100:101] offset:2048
	s_add_u32 s100, s100, 0x1000
	s_addc_u32 s101, s101, 0
	global_load_dword v128, v5, s[100:101]
	global_load_dword v129, v5, s[100:101] offset:2048
	s_add_u32 s100, s100, 0x1000
	s_addc_u32 s101, s101, 0
	global_load_dword v130, v5, s[100:101]
	global_load_dword v131, v5, s[100:101] offset:2048
	s_add_u32 s100, s100, 0x1000
	s_addc_u32 s101, s101, 0
	global_load_dword v132, v5, s[100:101]
	global_load_dword v133, v5, s[100:101] offset:2048
	s_add_u32 s100, s100, 0x1000
	s_addc_u32 s101, s101, 0
	global_load_dword v134, v5, s[100:101]
	global_load_dword v135, v5, s[100:101] offset:2048
	global_load_dword v136, v5, s[78:79]
	global_load_dword v137, v5, s[78:79] offset:2048
	s_waitcnt vmcnt(17)
	ds_write_b32 v5, v120
	s_waitcnt vmcnt(16)
	ds_write_b32 v5, v121 offset:2048
	s_waitcnt vmcnt(15)
	ds_write_b32 v5, v122 offset:4096
	s_waitcnt vmcnt(14)
	ds_write_b32 v5, v123 offset:6144
	s_waitcnt vmcnt(13)
	ds_write_b32 v5, v124 offset:8192
	s_waitcnt vmcnt(12)
	ds_write_b32 v5, v125 offset:10240
	s_waitcnt vmcnt(11)
	ds_write_b32 v5, v126 offset:12288
	s_waitcnt vmcnt(10)
	ds_write_b32 v5, v127 offset:14336
	s_waitcnt vmcnt(9)
	ds_write_b32 v5, v128 offset:16384
	s_waitcnt vmcnt(8)
	ds_write_b32 v5, v129 offset:18432
	s_waitcnt vmcnt(7)
	ds_write_b32 v5, v130 offset:20480
	s_waitcnt vmcnt(6)
	ds_write_b32 v5, v131 offset:22528
	s_waitcnt vmcnt(5)
	ds_write_b32 v5, v132 offset:24576
	s_waitcnt vmcnt(4)
	ds_write_b32 v5, v133 offset:26624
	s_waitcnt vmcnt(3)
	ds_write_b32 v5, v134 offset:28672
	s_waitcnt vmcnt(2)
	ds_write_b32 v5, v135 offset:30720
	s_waitcnt vmcnt(1)
	ds_write_b32 v5, v136 offset:32768
	s_waitcnt vmcnt(0)
	ds_write_b32 v5, v137 offset:34816
.LBB0_1230:
	v_and_b32_e32 v0, 0x3ff, v2
	v_ashrrev_i32_e32 v9, 31, v2
	v_mov_b32_e32 v8, v2
	v_and_b32_e32 v12, 0x3ff, v3
	v_lshlrev_b32_e32 v0, 2, v0
	v_ashrrev_i32_e32 v7, 31, v3
	v_mov_b32_e32 v6, v3
	v_lshl_add_u64 v[8:9], v[8:9], 2, s[74:75]
	v_lshl_add_u64 v[10:11], s[78:79], 0, v[0:1]
	v_cmp_gt_i32_e32 vcc, s63, v2
	v_lshlrev_b32_e32 v0, 2, v12
	v_lshl_add_u64 v[6:7], v[6:7], 2, s[74:75]
	v_lshl_add_u64 v[12:13], s[78:79], 0, v[0:1]
	v_cmp_gt_i32_e64 s[0:1], s63, v3
	v_cndmask_b32_e32 v9, v11, v9, vcc
	v_cndmask_b32_e32 v8, v10, v8, vcc
	ds_read_b32 v0, v5
	v_cndmask_b32_e64 v7, v13, v7, s[0:1]
	v_cndmask_b32_e64 v6, v12, v6, s[0:1]
	ds_read_b32 v8, v5 offset:2048
	v_add_u32_e32 v4, -2, v4
	v_cmp_eq_u32_e32 vcc, 0, v4
	s_or_b64 s[6:7], vcc, s[6:7]
	v_add_u32_e32 v2, 0x400, v2
	v_add_u32_e32 v3, 0x400, v3
	s_waitcnt lgkmcnt(0)
	v_mul_f32_e32 v6, 0xbfb8aa3b, v0
	v_fma_f32 v9, v0, s55, -v6
	v_rndne_f32_e32 v10, v6
	v_mul_f32_e32 v7, 0xbfb8aa3b, v8
	v_fma_f32 v11, v8, s55, -v7
	v_rndne_f32_e32 v12, v7
	v_fmac_f32_e32 v9, 0xb2a5705f, v0
	v_sub_f32_e32 v6, v6, v10
	v_fmac_f32_e32 v11, 0xb2a5705f, v8
	v_sub_f32_e32 v7, v7, v12
	v_add_f32_e32 v6, v6, v9
	v_cvt_i32_f32_e32 v10, v10
	v_exp_f32_e32 v6, v6
	v_add_f32_e32 v7, v7, v11
	v_cvt_i32_f32_e32 v12, v12
	v_exp_f32_e32 v7, v7
	v_ldexp_f32 v6, v6, v10
	v_cmp_nlt_f32_e32 vcc, s57, v0
	v_cmp_nlt_f32_e64 s[0:1], s57, v8
	v_ldexp_f32 v7, v7, v12
	v_cndmask_b32_e32 v6, 0, v6, vcc
	v_cmp_ngt_f32_e32 vcc, s58, v0
	v_cndmask_b32_e64 v7, 0, v7, s[0:1]
	s_nop 0
	v_cndmask_b32_e32 v6, v225, v6, vcc
	v_cmp_ngt_f32_e32 vcc, s58, v8
	s_nop 1
	v_cndmask_b32_e32 v7, v225, v7, vcc
	v_pk_add_f32 v[6:7], v[6:7], 1.0 op_sel_hi:[1,0]
	s_nop 0
	v_div_scale_f32 v9, s[0:1], v7, v7, v8
	v_div_scale_f32 v11, s[0:1], v6, v6, v0
	v_rcp_f32_e32 v13, v9
	v_rcp_f32_e32 v14, v11
	v_div_scale_f32 v10, vcc, v8, v7, v8
	v_fma_f32 v15, -v9, v13, 1.0
	v_fma_f32 v16, -v11, v14, 1.0
	v_fmac_f32_e32 v13, v15, v13
	v_div_scale_f32 v12, s[0:1], v0, v6, v0
	v_fmac_f32_e32 v14, v16, v14
	v_mul_f32_e32 v15, v10, v13
	v_mul_f32_e32 v16, v12, v14
	v_fma_f32 v17, -v9, v15, v10
	v_fma_f32 v18, -v11, v16, v12
	v_fmac_f32_e32 v15, v17, v13
	v_fmac_f32_e32 v16, v18, v14
	v_fma_f32 v9, -v9, v15, v10
	v_fma_f32 v10, -v11, v16, v12
	v_div_fmas_f32 v9, v9, v13, v15
	s_mov_b64 vcc, s[0:1]
	v_div_fixup_f32 v7, v9, v7, v8
	v_div_fmas_f32 v8, v10, v14, v16
	v_div_fixup_f32 v0, v8, v6, v0
	ds_write2st64_b32 v5, v0, v7 offset1:8
	v_add_u32_e32 v5, 0x1000, v5
	s_andn2_b64 exec, exec, s[6:7]
	s_cbranch_execnz .LBB0_1230
	s_or_b64 exec, exec, s[6:7]
	s_mov_b64 s[0:1], 0
	s_and_saveexec_b64 s[6:7], s[44:45]
	s_mov_b64 s[0:1], exec
	v_lshlrev_b32_e32 v0, 2, v97
	s_or_b64 exec, exec, s[6:7]
	s_orn2_b64 s[0:1], s[0:1], exec
	v_mov_b32_e32 v2, v97
